# v30 + M4 HGRN2 summary chunk loop: next chunk's 16 loads issued at the top of the chunk into a second register set (moved into place after a wait at chunk end) instead of just before the short state-u
# baseline (speedup 1.0000x reference)
; #define LAS __attribute__((address_space(3)))
; template <int TYPE, bool FULL>
; __device__ __forceinline__ void la_segment(const Frame& F, int item, const bf16* P, const float* GG, const float* LBl, const float* gn, float* SLOC, float* LDT, const float* SIN, bf16* Y) {
;     ...
;         { bf16x8 bv[NVT][2];
; #pragma unroll
;           for (int vt = 0; vt < NVT; ++vt)
; #pragma unroll
;               for (int ks = 0; ks < 2; ++ks) bv[vt][ks] = *(const LAS bf16x8*)(L + LA_VT + ((w * NVT + vt) * 16 + l15) * TS + (32 * ks + 8 * g4) * 2);
; #pragma unroll
;           for (int dt = 0; dt < 8; ++dt) { const f32x4 dec = *(const LAS f32x4*)(L + LA_DEC + (dt * 16 + 4 * g4) * 4);
;               const bf16x8 a0 = *(const LAS bf16x8*)(L + LA_KHT + (dt * 16 + l15) * TS + (8 * g4) * 2), a1 = *(const LAS bf16x8*)(L + LA_KHT + (dt * 16 + l15) * TS + (32 + 8 * g4) * 2);
; #pragma unroll
;               for (int vt = 0; vt < NVT; ++vt) { f32x4 sv = S[vt][dt] * dec; sv = __builtin_amdgcn_mfma_f32_16x16x32_bf16(a0, bv[vt][0], sv, 0, 0, 0); S[vt][dt] = __builtin_amdgcn_mfma_f32_16x16x32_bf16(a1, bv[vt][1], sv, 0, 0, 0); } } }
.LBB0_1579:
	v_add_u32_e32 v70, 0, v56
	s_waitcnt lgkmcnt(0)
	s_barrier
	v_add_u32_e32 v82, 0x22e00, v70
	v_pk_add_f32 v[44:45], v[44:45], v[36:37]
	ds_read_b128 v[36:39], v60
	ds_read_b128 v[40:43], v60 offset:64
	ds_read_b128 v[70:73], v82
	ds_read_b128 v[74:77], v61
	ds_read_b128 v[78:81], v61 offset:64
	s_add_i32 s21, s21, 64
	s_cmpk_eq_i32 s21, 0x400
	s_waitcnt lgkmcnt(2)
	v_pk_mul_f32 v[2:3], v[2:3], v[70:71]
	v_pk_mul_f32 v[4:5], v[4:5], v[72:73]
	s_waitcnt lgkmcnt(1)
	s_nop 0
	v_mfma_f32_16x16x32_bf16 v[2:5], v[74:77], v[36:39], v[2:5]
	s_waitcnt lgkmcnt(0)
	v_mfma_f32_16x16x32_bf16 v[2:5], v[78:81], v[40:43], v[2:5]
	ds_read_b128 v[70:73], v82 offset:64
	ds_read_b128 v[74:77], v61 offset:2304
	ds_read_b128 v[78:81], v61 offset:2368
	s_waitcnt lgkmcnt(2)
	v_pk_mul_f32 v[30:31], v[30:31], v[70:71]
	v_pk_mul_f32 v[32:33], v[32:33], v[72:73]
	s_waitcnt lgkmcnt(1)
	s_nop 0
	v_mfma_f32_16x16x32_bf16 v[30:33], v[74:77], v[36:39], v[30:33]
	s_waitcnt lgkmcnt(0)
	v_mfma_f32_16x16x32_bf16 v[30:33], v[78:81], v[40:43], v[30:33]
	ds_read_b128 v[70:73], v82 offset:128
	ds_read_b128 v[74:77], v61 offset:4608
	ds_read_b128 v[78:81], v61 offset:4672
	s_waitcnt lgkmcnt(2)
	v_pk_mul_f32 v[22:23], v[22:23], v[70:71]
	v_pk_mul_f32 v[24:25], v[24:25], v[72:73]
	s_waitcnt lgkmcnt(1)
	s_nop 0
	v_mfma_f32_16x16x32_bf16 v[22:25], v[74:77], v[36:39], v[22:25]
	s_waitcnt lgkmcnt(0)
	v_mfma_f32_16x16x32_bf16 v[22:25], v[78:81], v[40:43], v[22:25]
	ds_read_b128 v[70:73], v82 offset:192
	ds_read_b128 v[74:77], v61 offset:6912
	ds_read_b128 v[78:81], v61 offset:6976
	s_waitcnt lgkmcnt(2)
	v_pk_mul_f32 v[26:27], v[26:27], v[70:71]
	v_pk_mul_f32 v[28:29], v[28:29], v[72:73]
	s_waitcnt lgkmcnt(1)
	s_nop 0
	v_mfma_f32_16x16x32_bf16 v[26:29], v[74:77], v[36:39], v[26:29]
	s_waitcnt lgkmcnt(0)
	v_mfma_f32_16x16x32_bf16 v[26:29], v[78:81], v[40:43], v[26:29]
	ds_read_b128 v[70:73], v82 offset:256
	ds_read_b128 v[74:77], v61 offset:9216
	ds_read_b128 v[78:81], v61 offset:9280
	s_waitcnt lgkmcnt(2)
	v_pk_mul_f32 v[18:19], v[18:19], v[70:71]
	v_pk_mul_f32 v[20:21], v[20:21], v[72:73]
	s_waitcnt lgkmcnt(1)
	s_nop 0
	v_mfma_f32_16x16x32_bf16 v[18:21], v[74:77], v[36:39], v[18:21]
	s_waitcnt lgkmcnt(0)
	v_mfma_f32_16x16x32_bf16 v[18:21], v[78:81], v[40:43], v[18:21]
	ds_read_b128 v[70:73], v82 offset:320
	ds_read_b128 v[74:77], v61 offset:11520
	ds_read_b128 v[78:81], v61 offset:11584
	s_waitcnt lgkmcnt(2)
	v_pk_mul_f32 v[10:11], v[10:11], v[70:71]
	v_pk_mul_f32 v[12:13], v[12:13], v[72:73]
	s_waitcnt lgkmcnt(1)
	s_nop 0
	v_mfma_f32_16x16x32_bf16 v[10:13], v[74:77], v[36:39], v[10:13]
	s_waitcnt lgkmcnt(0)
	v_mfma_f32_16x16x32_bf16 v[10:13], v[78:81], v[40:43], v[10:13]
	ds_read_b128 v[70:73], v82 offset:384
	ds_read_b128 v[74:77], v61 offset:13824
	ds_read_b128 v[78:81], v61 offset:13888
	s_waitcnt lgkmcnt(2)
	v_pk_mul_f32 v[6:7], v[6:7], v[70:71]
	v_pk_mul_f32 v[8:9], v[8:9], v[72:73]
	s_waitcnt lgkmcnt(1)
	s_nop 0
	v_mfma_f32_16x16x32_bf16 v[6:9], v[74:77], v[36:39], v[6:9]
	s_waitcnt lgkmcnt(0)
	v_mfma_f32_16x16x32_bf16 v[6:9], v[78:81], v[40:43], v[6:9]
	ds_read_b128 v[70:73], v82 offset:448
	ds_read_b128 v[74:77], v61 offset:16128
	ds_read_b128 v[78:81], v61 offset:16192
	s_waitcnt lgkmcnt(2)
	v_pk_mul_f32 v[14:15], v[14:15], v[70:71]
	v_pk_mul_f32 v[16:17], v[16:17], v[72:73]
	s_waitcnt lgkmcnt(1)
	s_nop 0
	v_mfma_f32_16x16x32_bf16 v[14:17], v[74:77], v[36:39], v[14:17]
	s_waitcnt lgkmcnt(0)
	v_mfma_f32_16x16x32_bf16 v[14:17], v[78:81], v[40:43], v[14:17]
	s_waitcnt vmcnt(0)
	v_mov_b32_e32 v47, v195
	v_mov_b32_e32 v48, v196
	v_mov_b32_e32 v49, v197
	v_mov_b32_e32 v50, v198
	v_mov_b32_e32 v51, v199
	v_mov_b32_e32 v52, v200
	v_mov_b32_e32 v54, v201
	v_mov_b32_e32 v57, v202
	v_mov_b32_e32 v62, v203
	v_mov_b32_e32 v63, v204
	v_mov_b32_e32 v64, v205
	v_mov_b32_e32 v65, v206
	v_mov_b32_e32 v66, v207
	v_mov_b32_e32 v67, v208
	v_mov_b32_e32 v68, v209
	v_mov_b32_e32 v69, v210
	s_cbranch_scc1 .LBB0_1584
.LBB0_1580:
	s_cmpk_eq_i32 s21, 0x3c0
	s_cbranch_scc1 .Lh4_nopf
	s_add_i32 s35, s19, s21
	s_mul_hi_i32 s50, s35, 0x4800
	s_mulk_i32 s35, 0x4800
	s_add_u32 s35, s6, s35
	s_addc_u32 s52, s10, s50
	s_add_u32 s50, s35, s29
	s_addc_u32 s51, s52, 0
	v_lshlrev_b32_e32 v250, 1, v34
	global_load_dword v195, v250, s[50:51]
	s_add_u32 s50, s35, s34
	s_addc_u32 s51, s52, 0
	s_add_u32 s53, s35, 0x4800
	s_addc_u32 s54, s52, 0
	global_load_dword v196, v250, s[50:51]
	s_add_u32 s50, s53, s29
	s_addc_u32 s51, s54, 0
	global_load_dword v197, v250, s[50:51]
	s_add_u32 s50, s53, s34
	s_addc_u32 s51, s54, 0
	s_add_u32 s53, s35, 0x9000
	s_addc_u32 s54, s52, 0
	global_load_dword v198, v250, s[50:51]
	s_add_u32 s50, s53, s29
	s_addc_u32 s51, s54, 0
	global_load_dword v199, v250, s[50:51]
	s_add_u32 s50, s53, s34
	s_addc_u32 s51, s54, 0
	s_add_u32 s53, s35, 0xd800
	s_addc_u32 s54, s52, 0
	global_load_dword v200, v250, s[50:51]
	s_add_u32 s50, s53, s29
	s_addc_u32 s51, s54, 0
	global_load_dword v201, v250, s[50:51]
	s_add_u32 s50, s53, s34
	s_addc_u32 s51, s54, 0
	s_add_u32 s53, s35, 0x12000
	s_addc_u32 s54, s52, 0
	global_load_dword v202, v250, s[50:51]
	s_add_u32 s50, s53, s29
	s_addc_u32 s51, s54, 0
	global_load_dword v203, v250, s[50:51]
	s_add_u32 s50, s53, s34
	s_addc_u32 s51, s54, 0
	s_add_u32 s53, s35, 0x16800
	s_addc_u32 s54, s52, 0
	global_load_dword v204, v250, s[50:51]
	s_add_u32 s50, s53, s29
	s_addc_u32 s51, s54, 0
	global_load_dword v205, v250, s[50:51]
	s_add_u32 s50, s53, s34
	s_addc_u32 s51, s54, 0
	s_add_u32 s53, s35, 0x1b000
	s_addc_u32 s54, s52, 0
	global_load_dword v206, v250, s[50:51]
	s_add_u32 s50, s53, s29
	s_addc_u32 s51, s54, 0
	global_load_dword v207, v250, s[50:51]
	s_add_u32 s50, s53, s34
	s_addc_u32 s51, s54, 0
	s_add_u32 s35, s35, 0x1f800
	s_addc_u32 s52, s52, 0
	global_load_dword v208, v250, s[50:51]
	s_add_u32 s50, s35, s29
	s_addc_u32 s51, s52, 0
	global_load_dword v209, v250, s[50:51]
	s_add_u32 s50, s35, s34
	s_addc_u32 s51, s52, 0
	global_load_dword v210, v250, s[50:51]
; #define LAS __attribute__((address_space(3)))
; template <int TYPE, bool FULL>
; __device__ __forceinline__ void la_segment(const Frame& F, int item, const bf16* P, const float* GG, const float* LBl, const float* gn, float* SLOC, float* LDT, const float* SIN, bf16* Y) {
;     ...
;         const int m0 = b * SEQ + (seg * NCH + ch) * 64, sb = w, t0 = 8 * sb, I = sb >> 1;
;         float ca[8], cb[8], ka[8], kb[8], qa[8], qb[8]; float ra = 0.f, rb = 0.f;
; #pragma unroll
;         for (int j = 0; j < 8; ++j) { float ga, gb;
;             if (TYPE == 0) { ga = gr[j].x; gb = gr[j].y; ka[j] = blo(kr[j]); kb[j] = bhi(kr[j]); qa[j] = blo(qr[j]); qb[j] = bhi(qr[j]); }
;             else { ga = blo(kr[j]); gb = bhi(kr[j]); ka[j] = 1.f - fexp(ga); kb[j] = 1.f - fexp(gb); qa[j] = blo(qr[j]); qb[j] = bhi(qr[j]); }
;             ra += ga; rb += gb; ca[j] = ra; cb[j] = rb; }
;         *(LAS f32x2*)(L + LA_T8 + (sb * 128 + 2 * p) * 4) = (f32x2){ra, rb};
;         LA_BAR();
;         float brefa[5], brefb[5]; brefa[0] = 0.f; brefb[0] = 0.f; float cba = 0.f, cbb = 0.f;
; #pragma unroll
;         for (int J = 0; J < 4; ++J) { const f32x2 u0 = *(const LAS f32x2*)(L + LA_T8 + ((2 * J) * 128 + 2 * p) * 4), u1 = *(const LAS f32x2*)(L + LA_T8 + ((2 * J + 1) * 128 + 2 * p) * 4);
;             brefa[J + 1] = brefa[J] + (u0.x + u1.x); brefb[J + 1] = brefb[J] + (u0.y + u1.y);
;             if (sb == 2 * J + 1) { cba = u0.x; cbb = u0.y; } }
;         const float bIa = I == 0 ? brefa[0] : (I == 1 ? brefa[1] : (I == 2 ? brefa[2] : brefa[3])), bIb = I == 0 ? brefb[0] : (I == 1 ? brefb[1] : (I == 2 ? brefb[2] : brefb[3]));
;         const float bla = brefa[4], blb = brefb[4];
;         ldsa += bla; ldsb += blb;
;         const float eha = fexp(bla - bIa), ehb = fexp(blb - bIb);
;         const float eqa = fexp(bIa), eqb = fexp(bIb);
;         unsigned kh_a[4], kh_b[4], vlo[4], vhi[4], v2lo[4], v2hi[4];
;         float kfa[4], kfb[4];
; #pragma unroll
;         for (int Ip = 0; Ip < 4; ++Ip) { kfa[Ip] = fexp(fminf(brefa[Ip] - bIa, 0.f)); kfb[Ip] = fexp(fminf(brefb[Ip] - bIb, 0.f)); }
; #pragma unroll
;         for (int j = 0; j < 8; ++j) { const int t = t0 + j;
;             const float cca = fmaxf(cba + ca[j], -60.f), ccb = fmaxf(cbb + cb[j], -60.f); const float e1a = fexp(cca), e1b = fexp(ccb), e2a = fexp(-cca), e2b = fexp(-ccb);
;             const float kka = ka[j] * e2a, kkb = kb[j] * e2b;
.Lh4_nopf:
	v_lshlrev_b32_e32 v36, 16, v47
	v_and_b32_e32 v37, 0xffff0000, v47
	v_lshlrev_b32_e32 v38, 16, v49
	v_and_b32_e32 v39, 0xffff0000, v49
	v_lshlrev_b32_e32 v42, 16, v54
	v_mul_f32_e32 v75, 0x3fb8aa3b, v36
	v_pk_add_f32 v[82:83], v[36:37], 0 op_sel_hi:[1,0]
	v_exp_f32_e32 v78, v75
	v_mul_f32_e32 v79, 0x3fb8aa3b, v38
	v_pk_add_f32 v[86:87], v[82:83], v[38:39]
	v_mul_f32_e32 v38, 0x3fb8aa3b, v42
	v_exp_f32_e32 v38, v38
	v_lshlrev_b32_e32 v40, 16, v51
	v_and_b32_e32 v41, 0xffff0000, v51
	v_and_b32_e32 v71, 0xffff0000, v62
	v_sub_f32_e32 v84, 1.0, v78
	v_mul_f32_e32 v78, 0x3fb8aa3b, v37
	v_mul_f32_e32 v36, 0x3fb8aa3b, v40
	v_mul_f32_e32 v37, 0x3fb8aa3b, v41
	v_exp_f32_e32 v36, v36
	v_exp_f32_e32 v37, v37
	v_sub_f32_e32 v104, 1.0, v38
	v_mul_f32_e32 v38, 0x3fb8aa3b, v71
	v_exp_f32_e32 v38, v38
	v_and_b32_e32 v43, 0xffff0000, v54
	v_lshlrev_b32_e32 v70, 16, v62
	v_lshlrev_b32_e32 v74, 16, v66
	v_mul_f32_e32 v80, 0x3fb8aa3b, v39
	v_sub_f32_e32 v39, 1.0, v36
	v_sub_f32_e32 v103, 1.0, v37
	v_mul_f32_e32 v36, 0x3fb8aa3b, v43
	v_mul_f32_e32 v37, 0x3fb8aa3b, v70
	v_exp_f32_e32 v36, v36
	v_exp_f32_e32 v37, v37
	v_sub_f32_e32 v107, 1.0, v38
	v_mul_f32_e32 v38, 0x3fb8aa3b, v74
	v_pk_add_f32 v[88:89], v[86:87], v[40:41]
	v_exp_f32_e32 v38, v38
	v_pk_add_f32 v[90:91], v[88:89], v[42:43]
	v_lshlrev_b32_e32 v72, 16, v64
	v_and_b32_e32 v73, 0xffff0000, v64
	v_pk_add_f32 v[92:93], v[90:91], v[70:71]
	v_and_b32_e32 v75, 0xffff0000, v66
	v_and_b32_e32 v77, 0xffff0000, v68
	v_exp_f32_e32 v78, v78
	v_sub_f32_e32 v105, 1.0, v36
	v_sub_f32_e32 v106, 1.0, v37
	v_mul_f32_e32 v36, 0x3fb8aa3b, v72
	v_mul_f32_e32 v37, 0x3fb8aa3b, v73
	v_pk_add_f32 v[94:95], v[92:93], v[72:73]
	v_lshlrev_b32_e32 v76, 16, v68
	v_exp_f32_e32 v36, v36
	v_exp_f32_e32 v37, v37
	v_sub_f32_e32 v110, 1.0, v38
	v_pk_add_f32 v[96:97], v[94:95], v[74:75]
	v_mul_f32_e32 v38, 0x3fb8aa3b, v77
	v_exp_f32_e32 v74, v38
	v_pk_add_f32 v[98:99], v[96:97], v[76:77]
	v_add_u32_e32 v38, s12, v53
	ds_write_b64 v38, v[98:99]
	v_add_u32_e32 v38, 0, v53
	v_sub_f32_e32 v100, 1.0, v78
	s_waitcnt lgkmcnt(0)
	s_barrier
	v_add_u32_e32 v78, 0x23000, v38
	v_sub_f32_e32 v108, 1.0, v36
	v_sub_f32_e32 v109, 1.0, v37
	v_mul_f32_e32 v36, 0x3fb8aa3b, v75
	v_mul_f32_e32 v37, 0x3fb8aa3b, v76
	ds_read2st64_b64 v[40:43], v78 offset1:1
	ds_read2st64_b64 v[70:73], v78 offset0:2 offset1:3
	v_exp_f32_e32 v36, v36
	v_exp_f32_e32 v37, v37
	v_sub_f32_e32 v113, 1.0, v74
	ds_read2st64_b64 v[74:77], v78 offset0:4 offset1:5
	v_exp_f32_e32 v79, v79
	v_exp_f32_e32 v80, v80
	v_sub_f32_e32 v111, 1.0, v36
	v_sub_f32_e32 v112, 1.0, v37
	s_waitcnt lgkmcnt(2)
	v_cndmask_b32_e64 v36, 0, v41, s[42:43]
	v_cndmask_b32_e64 v37, 0, v40, s[42:43]
	s_waitcnt lgkmcnt(1)
	v_cndmask_b32_e64 v36, v36, v71, s[44:45]
	v_cndmask_b32_e64 v37, v37, v70, s[44:45]
	s_waitcnt lgkmcnt(0)
	v_cndmask_b32_e64 v114, v36, v75, s[46:47]
	v_cndmask_b32_e64 v115, v37, v74, s[46:47]
	v_pk_add_f32 v[36:37], v[40:41], v[42:43]
	v_sub_f32_e32 v101, 1.0, v79
	v_sub_f32_e32 v102, 1.0, v80
	ds_read2st64_b64 v[78:81], v78 offset0:6 offset1:7
	v_pk_add_f32 v[40:41], v[36:37], 0 op_sel_hi:[1,0]
	v_pk_add_f32 v[36:37], v[70:71], v[72:73]
	v_lshrrev_b32_e32 v72, 16, v48
	v_pk_add_f32 v[42:43], v[40:41], v[36:37]
	v_pk_add_f32 v[36:37], v[74:75], v[76:77]
	s_waitcnt lgkmcnt(0)
	v_cndmask_b32_e64 v73, v114, v79, s[48:49]
	v_pk_add_f32 v[70:71], v[42:43], v[36:37]
	v_pk_add_f32 v[36:37], v[78:79], v[80:81]
	v_cndmask_b32_e64 v42, v70, v42, s[40:41]
	v_cndmask_b32_e64 v40, v42, v40, s[38:39]
	v_cndmask_b32_e64 v42, v71, v43, s[40:41]
	v_cndmask_b32_e64 v41, v42, v41, s[38:39]
	v_pk_add_f32 v[36:37], v[70:71], v[36:37]
	v_cndmask_b32_e64 v41, v41, 0, s[36:37]
	v_sub_f32_e32 v41, v37, v41
	v_mul_f32_e32 v41, 0x3fb8aa3b, v41
	v_exp_f32_e32 v43, v41
	v_add_f32_e32 v41, v83, v73
	v_max_f32_e32 v41, 0xc2700000, v41
	v_cndmask_b32_e64 v77, v115, v78, s[48:49]
	v_mul_f32_e32 v41, 0xbfb8aa3b, v41
	v_exp_f32_e32 v41, v41
	v_add_f32_e32 v42, v82, v77
	v_cndmask_b32_e64 v40, v40, 0, s[36:37]
	v_max_f32_e32 v42, 0xc2700000, v42
	v_sub_f32_e32 v40, v36, v40
	v_mul_f32_e32 v42, 0xbfb8aa3b, v42
	v_mul_f32_e32 v40, 0x3fb8aa3b, v40
	v_exp_f32_e32 v42, v42
	v_exp_f32_e32 v81, v40
	v_mul_f32_e32 v40, v100, v41
	v_mul_f32_e32 v40, v40, v43
	v_cvt_pk_bf16_f32 v40, v40, 0
	v_mul_f32_e32 v41, v84, v42
	v_and_b32_e32 v42, 0xffff, v40
	v_add_f32_e32 v40, v87, v73
	v_max_f32_e32 v40, 0xc2700000, v40
	v_add_f32_e32 v70, v86, v77
	v_mul_f32_e32 v40, 0xbfb8aa3b, v40
	v_max_f32_e32 v70, 0xc2700000, v70
	v_exp_f32_e32 v40, v40
	v_mul_f32_e32 v70, 0xbfb8aa3b, v70
	v_exp_f32_e32 v70, v70
	v_mul_f32_e32 v41, v41, v81
	v_mul_f32_e32 v40, v102, v40
	v_mul_f32_e32 v74, v40, v43
	v_mul_f32_e32 v40, v101, v70
	v_cvt_pk_bf16_f32 v41, v41, 0
	v_mul_f32_e32 v40, v40, v81
	v_and_b32_e32 v41, 0xffff, v41
	v_cvt_pk_bf16_f32 v40, v40, 0
	v_lshl_or_b32 v40, v40, 16, v41
	v_cvt_pk_bf16_f32 v41, v74, 0
	v_lshl_or_b32 v70, v41, 16, v42
	v_add_f32_e32 v41, v89, v73
	v_max_f32_e32 v41, 0xc2700000, v41
	v_mul_f32_e32 v41, 0xbfb8aa3b, v41
	v_exp_f32_e32 v41, v41
	v_add_f32_e32 v42, v88, v77
	v_max_f32_e32 v42, 0xc2700000, v42
	v_mul_f32_e32 v42, 0xbfb8aa3b, v42
	v_exp_f32_e32 v42, v42
	v_mul_f32_e32 v41, v103, v41
	v_mul_f32_e32 v41, v41, v43
	v_cvt_pk_bf16_f32 v41, v41, 0
; template <int TYPE, bool FULL>
; __device__ __forceinline__ void la_segment(const Frame& F, int item, const bf16* P, const float* GG, const float* LBl, const float* gn, float* SLOC, float* LDT, const float* SIN, bf16* Y) {
;     ...
; #pragma unroll
;         for (int Ip = 0; Ip < 4; ++Ip) { kfa[Ip] = fexp(fminf(brefa[Ip] - bIa, 0.f)); kfb[Ip] = fexp(fminf(brefb[Ip] - bIb, 0.f)); }
; #pragma unroll
;         for (int j = 0; j < 8; ++j) { const int t = t0 + j;
;             const float cca = fmaxf(cba + ca[j], -60.f), ccb = fmaxf(cbb + cb[j], -60.f); const float e1a = fexp(cca), e1b = fexp(ccb), e2a = fexp(-cca), e2b = fexp(-ccb);
;             const float kka = ka[j] * e2a, kkb = kb[j] * e2b;
;             const float kha = kka * eha, khb = kkb * ehb;
;             if (j & 1) { kh_a[j >> 1] |= f2bf(kha) << 16; kh_b[j >> 1] |= f2bf(khb) << 16; } else { kh_a[j >> 1] = f2bf(kha); kh_b[j >> 1] = f2bf(khb); }
;             if (FULL) { const float qpa = qa[j] * e1a, qpb = qb[j] * e1b;
;                 *(LAS unsigned*)(L + LA_QP + t * QS + 4 * p) = pk2(qpa, qpb); *(LAS unsigned*)(L + LA_QT + t * QS + 4 * p) = pk2(qpa * eqa, qpb * eqb);
; #pragma unroll
;                 for (int Ip = 0; Ip < 4; ++Ip) if (Ip >= I) { const int base = Ip == 0 ? 0 : (Ip == 1 ? 16 : (Ip == 2 ? 48 : 96));
;                     *(LAS unsigned*)(L + LA_KP + (base + t) * QS + 4 * p) = pk2(kka * kfa[Ip], kkb * kfb[Ip]); } }
;             const unsigned x = vr[j].x, y = vr[j].y;
;             if (j & 1) { vlo[j >> 1] |= x << 16; vhi[j >> 1] |= x & 0xffff0000u; v2lo[j >> 1] |= y << 16; v2hi[j >> 1] |= y & 0xffff0000u; }
;             else { vlo[j >> 1] = x & 0xffffu; vhi[j >> 1] = x >> 16; v2lo[j >> 1] = y & 0xffffu; v2hi[j >> 1] = y >> 16; } }
;         *(LAS v4u*)(L + LA_KHT + (2 * p) * TS + 2 * t0) = (v4u){kh_a[0], kh_a[1], kh_a[2], kh_a[3]}; *(LAS v4u*)(L + LA_KHT + (2 * p + 1) * TS + 2 * t0) = (v4u){kh_b[0], kh_b[1], kh_b[2], kh_b[3]};
;         if (DV == 256) { *(LAS v4u*)(L + LA_VT + (4 * p) * TS + 2 * t0) = (v4u){vlo[0], vlo[1], vlo[2], vlo[3]}; *(LAS v4u*)(L + LA_VT + (4 * p + 1) * TS + 2 * t0) = (v4u){vhi[0], vhi[1], vhi[2], vhi[3]};
;                          *(LAS v4u*)(L + LA_VT + (4 * p + 2) * TS + 2 * t0) = (v4u){v2lo[0], v2lo[1], v2lo[2], v2lo[3]}; *(LAS v4u*)(L + LA_VT + (4 * p + 3) * TS + 2 * t0) = (v4u){v2hi[0], v2hi[1], v2hi[2], v2hi[3]}; }
	v_and_b32_e32 v71, 0xffff, v48
	v_mul_f32_e32 v39, v39, v42
	v_and_b32_e32 v42, 0xffff, v41
	v_add_f32_e32 v41, v91, v73
	v_lshl_or_b32 v74, v50, 16, v71
	v_max_f32_e32 v41, 0xc2700000, v41
	v_add_f32_e32 v71, v90, v77
	v_mul_f32_e32 v41, 0xbfb8aa3b, v41
	v_max_f32_e32 v71, 0xc2700000, v71
	v_exp_f32_e32 v41, v41
	v_mul_f32_e32 v71, 0xbfb8aa3b, v71
	v_exp_f32_e32 v71, v71
	v_mul_f32_e32 v39, v39, v81
	v_mul_f32_e32 v41, v105, v41
	v_mul_f32_e32 v75, v41, v43
	v_mul_f32_e32 v41, v104, v71
	v_cvt_pk_bf16_f32 v39, v39, 0
	v_mul_f32_e32 v41, v41, v81
	v_and_b32_e32 v39, 0xffff, v39
	v_cvt_pk_bf16_f32 v41, v41, 0
	v_lshl_or_b32 v41, v41, 16, v39
	v_cvt_pk_bf16_f32 v39, v75, 0
	v_and_or_b32 v78, v50, s17, v72
	v_and_b32_e32 v72, 0xffff, v52
	v_lshl_or_b32 v71, v39, 16, v42
	v_add_f32_e32 v39, v93, v73
	v_add_f32_e32 v42, v92, v77
	v_lshl_or_b32 v75, v57, 16, v72
	v_max_f32_e32 v39, 0xc2700000, v39
	v_max_f32_e32 v42, 0xc2700000, v42
	v_add_f32_e32 v72, v95, v73
	v_add_f32_e32 v80, v94, v77
	v_mul_f32_e32 v39, 0xbfb8aa3b, v39
	v_mul_f32_e32 v42, 0xbfb8aa3b, v42
	v_max_f32_e32 v72, 0xc2700000, v72
	v_max_f32_e32 v80, 0xc2700000, v80
	v_exp_f32_e32 v39, v39
	v_exp_f32_e32 v42, v42
	v_mul_f32_e32 v72, 0xbfb8aa3b, v72
	v_mul_f32_e32 v80, 0xbfb8aa3b, v80
	v_exp_f32_e32 v72, v72
	v_exp_f32_e32 v80, v80
	v_mul_f32_e32 v39, v107, v39
	v_mul_f32_e32 v42, v106, v42
	v_mul_f32_e32 v39, v39, v43
	v_mul_f32_e32 v42, v42, v81
	v_mul_f32_e32 v72, v109, v72
	v_mul_f32_e32 v80, v108, v80
	v_cvt_pk_bf16_f32 v42, v42, 0
	v_cvt_pk_bf16_f32 v39, v39, 0
	v_mul_f32_e32 v72, v72, v43
	v_mul_f32_e32 v80, v80, v81
	v_and_b32_e32 v42, 0xffff, v42
	v_and_b32_e32 v39, 0xffff, v39
	v_cvt_pk_bf16_f32 v80, v80, 0
	v_cvt_pk_bf16_f32 v72, v72, 0
	v_lshl_or_b32 v42, v80, 16, v42
	v_lshl_or_b32 v72, v72, 16, v39
	v_add_f32_e32 v39, v97, v73
	v_add_f32_e32 v80, v96, v77
	v_add_f32_e32 v73, v99, v73
	v_max_f32_e32 v39, 0xc2700000, v39
	v_max_f32_e32 v80, 0xc2700000, v80
	v_max_f32_e32 v73, 0xc2700000, v73
	v_add_f32_e32 v77, v98, v77
	v_mul_f32_e32 v39, 0xbfb8aa3b, v39
	v_mul_f32_e32 v80, 0xbfb8aa3b, v80
	v_mul_f32_e32 v73, 0xbfb8aa3b, v73
	v_max_f32_e32 v77, 0xc2700000, v77
	v_exp_f32_e32 v39, v39
	v_exp_f32_e32 v83, v80
	v_exp_f32_e32 v73, v73
	v_mul_f32_e32 v77, 0xbfb8aa3b, v77
	v_exp_f32_e32 v77, v77
	v_lshrrev_b32_e32 v82, 16, v63
	v_and_or_b32 v80, v65, s17, v82
	v_mul_f32_e32 v39, v111, v39
	v_mul_f32_e32 v82, v110, v83
	v_mul_f32_e32 v73, v113, v73
	v_mul_f32_e32 v39, v39, v43
	v_mul_f32_e32 v82, v82, v81
	v_mul_f32_e32 v73, v73, v43
	v_mul_f32_e32 v43, v112, v77
	v_cvt_pk_bf16_f32 v82, v82, 0
	v_cvt_pk_bf16_f32 v39, v39, 0
	v_mul_f32_e32 v43, v43, v81
	v_lshrrev_b32_e32 v76, 16, v52
	v_and_b32_e32 v82, 0xffff, v82
	v_and_b32_e32 v39, 0xffff, v39
	v_cvt_pk_bf16_f32 v43, v43, 0
	v_cvt_pk_bf16_f32 v73, v73, 0
	v_and_or_b32 v79, v57, s17, v76
	v_and_b32_e32 v76, 0xffff, v63
	v_and_b32_e32 v83, 0xffff, v67
	v_lshrrev_b32_e32 v84, 16, v67
	v_lshl_or_b32 v43, v43, 16, v82
	v_lshl_or_b32 v73, v73, 16, v39
	v_add_u32_e32 v39, s13, v55
	v_lshl_or_b32 v76, v65, 16, v76
	v_and_or_b32 v81, v69, s17, v84
	v_lshl_or_b32 v77, v69, 16, v83
	ds_write_b128 v58, v[40:43]
	ds_write_b128 v39, v[70:73] offset:144
	ds_write_b128 v59, v[74:77]
	v_add_u32_e32 v39, s15, v55
	s_andn2_b64 vcc, exec, s[30:31]
	ds_write_b128 v39, v[78:81] offset:144
	s_cbranch_vccnz .LBB0_1582
	v_mul_f32_e32 v39, 0x3fb8aa3b, v36
	v_exp_f32_e32 v40, v39
	v_mul_f32_e32 v39, 0x3fb8aa3b, v37
	v_exp_f32_e32 v41, v39
	v_add_u32_e32 v38, 0x22e00, v38
	ds_write_b64 v38, v[40:41]
.LBB0_1582:
	s_branch .LBB0_1579
.LBB0_1584:
	s_mov_b32 s29, s25
	s_lshl_b64 s[12:13], s[28:29], 16
	s_add_u32 s12, s26, s12
	s_addc_u32 s13, s27, s13
	s_add_u32 s12, s12, 0x72400000
	v_or_b32_e32 v36, s11, v85
	s_addc_u32 s13, s13, 0
	v_ashrrev_i32_e32 v37, 31, v36
	v_lshl_add_u64 v[38:39], v[36:37], 4, s[12:13]
	global_store_dwordx4 v[38:39], v[2:5], off
	s_and_b64 vcc, exec, s[30:31]
	s_nop 0
	v_or_b32_e32 v2, 64, v36
	v_ashrrev_i32_e32 v3, 31, v2
	v_lshl_add_u64 v[2:3], v[2:3], 4, s[12:13]
	global_store_dwordx4 v[2:3], v[30:33], off
	v_or_b32_e32 v2, 0x80, v36
	v_ashrrev_i32_e32 v3, 31, v2
	v_lshl_add_u64 v[2:3], v[2:3], 4, s[12:13]
	global_store_dwordx4 v[2:3], v[22:25], off
	v_or_b32_e32 v2, 0xc0, v36
	v_ashrrev_i32_e32 v3, 31, v2
	v_lshl_add_u64 v[2:3], v[2:3], 4, s[12:13]
	global_store_dwordx4 v[2:3], v[26:29], off
	v_or_b32_e32 v2, 0x100, v36
	v_ashrrev_i32_e32 v3, 31, v2
	v_lshl_add_u64 v[2:3], v[2:3], 4, s[12:13]
	global_store_dwordx4 v[2:3], v[18:21], off
	v_or_b32_e32 v2, 0x140, v36
	v_ashrrev_i32_e32 v3, 31, v2
	v_lshl_add_u64 v[2:3], v[2:3], 4, s[12:13]
	global_store_dwordx4 v[2:3], v[10:13], off
	v_or_b32_e32 v2, 0x180, v36
	v_ashrrev_i32_e32 v3, 31, v2
	v_lshl_add_u64 v[2:3], v[2:3], 4, s[12:13]
	global_store_dwordx4 v[2:3], v[6:9], off
	v_or_b32_e32 v2, 0x1c0, v36
	v_ashrrev_i32_e32 v3, 31, v2
	v_lshl_add_u64 v[2:3], v[2:3], 4, s[12:13]
	global_store_dwordx4 v[2:3], v[14:17], off
	s_cbranch_vccz .LBB0_1586
	s_lshl_b64 s[12:13], s[28:29], 9
	s_add_u32 s12, s26, s12
	s_addc_u32 s13, s27, s13
	v_lshlrev_b32_e32 v34, 2, v34
	v_lshl_add_u64 v[2:3], s[12:13], 0, v[34:35]
	v_add_co_u32_e32 v2, vcc, 0x510000, v2
	s_nop 1
	v_addc_co_u32_e32 v3, vcc, 0, v3, vcc
	global_store_dwordx2 v[2:3], v[44:45], off
